# on top of v29: the six GEMM mainloop heads aligned to 64 bytes
# baseline (speedup 1.0000x reference)
; template <class Epi>
; DI void gemm_phase(LAS unsigned char* lds, const Gemm g, const StaticOrder& S, const Epi& E) {
;     ...
;         const bool has_next = S.next(ui + 1, nxt);
;         const char* nA = has_next ? (const char*)g.A + (size_t)nxt.pm * tstep : cA; const char* nB = has_next ? (const char*)g.Bt + (size_t)nxt.pn * tstep : cB;
;         for (int t = 0; t < nt; t += 2) {
;     ...
;         for (int a = 0; a < 2; ++a)
; #pragma unroll
;             for (int b = 0; b < 2; ++b)
; #pragma unroll
;                 for (int m = 0; m < 4; ++m)
; #pragma unroll
;                     for (int n = 0; n < 2; ++n) acc[a][b][m][n] = (f32x4){0.f, 0.f, 0.f, 0.f};
.LBB0_36:
	s_ashr_i32 s11, s10, 31
	v_mov_b64_e32 v[0:1], 0xb00
	s_lshl_b64 s[4:5], s[10:11], 20
	v_cmp_lt_i64_e32 vcc, s[14:15], v[0:1]
	s_add_u32 s14, s92, s4
	s_addc_u32 s15, s93, s5
	s_and_b64 s[4:5], vcc, exec
	s_cselect_b32 s4, s15, s19
	s_cselect_b32 s5, s14, s18
	s_ashr_i32 s9, s8, 31
	s_lshl_b64 s[16:17], s[8:9], 20
	s_add_u32 s16, s25, s16
	s_addc_u32 s17, s26, s17
	s_and_b64 s[22:23], vcc, exec
	s_cselect_b32 s9, s17, s21
	s_cselect_b32 s11, s16, s20
	s_add_u32 s18, s18, 0x80080
	s_addc_u32 s19, s19, 0
	s_add_u32 s33, s20, 0x100
	v_mov_b32_e32 v0, 0
	s_addc_u32 s37, s21, 0
	s_mov_b32 s38, -2
	v_mov_b32_e32 v1, v0
	v_mov_b32_e32 v2, v0
	v_mov_b32_e32 v3, v0
	v_mov_b32_e32 v4, v0
	v_mov_b32_e32 v5, v0
	v_mov_b32_e32 v6, v0
	v_mov_b32_e32 v7, v0
	v_mov_b32_e32 v16, v0
	v_mov_b32_e32 v17, v0
	v_mov_b32_e32 v18, v0
	v_mov_b32_e32 v19, v0
	v_mov_b32_e32 v20, v0
	v_mov_b32_e32 v21, v0
	v_mov_b32_e32 v22, v0
	v_mov_b32_e32 v23, v0
	v_mov_b32_e32 v32, v0
	v_mov_b32_e32 v33, v0
	v_mov_b32_e32 v34, v0
	v_mov_b32_e32 v35, v0
	v_mov_b32_e32 v36, v0
	v_mov_b32_e32 v37, v0
	v_mov_b32_e32 v38, v0
	v_mov_b32_e32 v39, v0
	v_mov_b32_e32 v48, v0
	v_mov_b32_e32 v49, v0
	v_mov_b32_e32 v50, v0
	v_mov_b32_e32 v51, v0
	v_mov_b32_e32 v52, v0
	v_mov_b32_e32 v53, v0
	v_mov_b32_e32 v54, v0
	v_mov_b32_e32 v55, v0
	v_mov_b32_e32 v8, v0
	v_mov_b32_e32 v9, v0
	v_mov_b32_e32 v10, v0
	v_mov_b32_e32 v11, v0
	v_mov_b32_e32 v12, v0
	v_mov_b32_e32 v13, v0
	v_mov_b32_e32 v14, v0
	v_mov_b32_e32 v15, v0
	v_mov_b32_e32 v24, v0
	v_mov_b32_e32 v25, v0
	v_mov_b32_e32 v26, v0
	v_mov_b32_e32 v27, v0
	v_mov_b32_e32 v28, v0
	v_mov_b32_e32 v29, v0
	v_mov_b32_e32 v30, v0
	v_mov_b32_e32 v31, v0
	v_mov_b32_e32 v40, v0
	v_mov_b32_e32 v41, v0
	v_mov_b32_e32 v42, v0
	v_mov_b32_e32 v43, v0
	v_mov_b32_e32 v44, v0
	v_mov_b32_e32 v45, v0
	v_mov_b32_e32 v46, v0
	v_mov_b32_e32 v47, v0
	v_mov_b32_e32 v56, v0
	v_mov_b32_e32 v57, v0
	v_mov_b32_e32 v58, v0
	v_mov_b32_e32 v59, v0
	v_mov_b32_e32 v60, v0
	v_mov_b32_e32 v61, v0
	v_mov_b32_e32 v62, v0
	v_mov_b32_e32 v63, v0
	v_mov_b32_e32 v64, v0
	v_mov_b32_e32 v65, v0
	v_mov_b32_e32 v66, v0
	v_mov_b32_e32 v67, v0
	v_mov_b32_e32 v68, v0
	v_mov_b32_e32 v69, v0
	v_mov_b32_e32 v70, v0
	v_mov_b32_e32 v71, v0
	v_mov_b32_e32 v80, v0
	v_mov_b32_e32 v81, v0
	v_mov_b32_e32 v82, v0
	v_mov_b32_e32 v83, v0
	v_mov_b32_e32 v84, v0
	v_mov_b32_e32 v85, v0
	v_mov_b32_e32 v86, v0
	v_mov_b32_e32 v87, v0
	v_mov_b32_e32 v96, v0
	v_mov_b32_e32 v97, v0
	v_mov_b32_e32 v98, v0
	v_mov_b32_e32 v99, v0
	v_mov_b32_e32 v100, v0
	v_mov_b32_e32 v101, v0
	v_mov_b32_e32 v102, v0
	v_mov_b32_e32 v103, v0
	v_mov_b32_e32 v112, v0
	v_mov_b32_e32 v113, v0
	v_mov_b32_e32 v114, v0
	v_mov_b32_e32 v115, v0
	v_mov_b32_e32 v116, v0
	v_mov_b32_e32 v117, v0
	v_mov_b32_e32 v118, v0
	v_mov_b32_e32 v119, v0
	v_mov_b32_e32 v72, v0
	v_mov_b32_e32 v73, v0
	v_mov_b32_e32 v74, v0
	v_mov_b32_e32 v75, v0
	v_mov_b32_e32 v76, v0
	v_mov_b32_e32 v77, v0
	v_mov_b32_e32 v78, v0
	v_mov_b32_e32 v79, v0
	v_mov_b32_e32 v88, v0
	v_mov_b32_e32 v89, v0
	v_mov_b32_e32 v90, v0
	v_mov_b32_e32 v91, v0
	v_mov_b32_e32 v92, v0
	v_mov_b32_e32 v93, v0
	v_mov_b32_e32 v94, v0
	v_mov_b32_e32 v95, v0
	v_mov_b32_e32 v104, v0
	v_mov_b32_e32 v105, v0
	v_mov_b32_e32 v106, v0
	v_mov_b32_e32 v107, v0
	v_mov_b32_e32 v108, v0
	v_mov_b32_e32 v109, v0
	v_mov_b32_e32 v110, v0
	v_mov_b32_e32 v111, v0
	v_mov_b32_e32 v120, v0
	v_mov_b32_e32 v121, v0
	v_mov_b32_e32 v122, v0
	v_mov_b32_e32 v123, v0
	v_mov_b32_e32 v124, v0
	v_mov_b32_e32 v125, v0
	v_mov_b32_e32 v126, v0
	v_mov_b32_e32 v127, v0
	.p2align	6

; template <class Epi>
; DI void gemm_phase(LAS unsigned char* lds, const Gemm g, const StaticOrder& S, const Epi& E) {
;     ...
;         for (int a = 0; a < 2; ++a)
; #pragma unroll
;             for (int b = 0; b < 2; ++b)
; #pragma unroll
;                 for (int m = 0; m < 4; ++m)
; #pragma unroll
;                     for (int n = 0; n < 2; ++n) acc[a][b][m][n] = (f32x4){0.f, 0.f, 0.f, 0.f};
.LBB0_76:
	s_add_u32 s4, s22, 0x100
	v_mov_b32_e32 v0, 0
	s_addc_u32 s5, s23, 0
	s_mov_b32 s33, -2
	v_mov_b32_e32 v1, v0
	v_mov_b32_e32 v2, v0
	v_mov_b32_e32 v3, v0
	v_mov_b32_e32 v4, v0
	v_mov_b32_e32 v5, v0
	v_mov_b32_e32 v6, v0
	v_mov_b32_e32 v7, v0
	v_mov_b32_e32 v8, v0
	v_mov_b32_e32 v9, v0
	v_mov_b32_e32 v10, v0
	v_mov_b32_e32 v11, v0
	v_mov_b32_e32 v12, v0
	v_mov_b32_e32 v13, v0
	v_mov_b32_e32 v14, v0
	v_mov_b32_e32 v15, v0
	v_mov_b32_e32 v16, v0
	v_mov_b32_e32 v17, v0
	v_mov_b32_e32 v18, v0
	v_mov_b32_e32 v19, v0
	v_mov_b32_e32 v20, v0
	v_mov_b32_e32 v21, v0
	v_mov_b32_e32 v22, v0
	v_mov_b32_e32 v23, v0
	v_mov_b32_e32 v24, v0
	v_mov_b32_e32 v25, v0
	v_mov_b32_e32 v26, v0
	v_mov_b32_e32 v27, v0
	v_mov_b32_e32 v28, v0
	v_mov_b32_e32 v29, v0
	v_mov_b32_e32 v30, v0
	v_mov_b32_e32 v31, v0
	v_mov_b32_e32 v64, v0
	v_mov_b32_e32 v65, v0
	v_mov_b32_e32 v66, v0
	v_mov_b32_e32 v67, v0
	v_mov_b32_e32 v68, v0
	v_mov_b32_e32 v69, v0
	v_mov_b32_e32 v70, v0
	v_mov_b32_e32 v71, v0
	v_mov_b32_e32 v72, v0
	v_mov_b32_e32 v73, v0
	v_mov_b32_e32 v74, v0
	v_mov_b32_e32 v75, v0
	v_mov_b32_e32 v76, v0
	v_mov_b32_e32 v77, v0
	v_mov_b32_e32 v78, v0
	v_mov_b32_e32 v79, v0
	v_mov_b32_e32 v80, v0
	v_mov_b32_e32 v81, v0
	v_mov_b32_e32 v82, v0
	v_mov_b32_e32 v83, v0
	v_mov_b32_e32 v84, v0
	v_mov_b32_e32 v85, v0
	v_mov_b32_e32 v86, v0
	v_mov_b32_e32 v87, v0
	v_mov_b32_e32 v88, v0
	v_mov_b32_e32 v89, v0
	v_mov_b32_e32 v90, v0
	v_mov_b32_e32 v91, v0
	v_mov_b32_e32 v92, v0
	v_mov_b32_e32 v93, v0
	v_mov_b32_e32 v94, v0
	v_mov_b32_e32 v95, v0
	v_mov_b32_e32 v32, v0
	v_mov_b32_e32 v33, v0
	v_mov_b32_e32 v34, v0
	v_mov_b32_e32 v35, v0
	v_mov_b32_e32 v36, v0
	v_mov_b32_e32 v37, v0
	v_mov_b32_e32 v38, v0
	v_mov_b32_e32 v39, v0
	v_mov_b32_e32 v40, v0
	v_mov_b32_e32 v41, v0
	v_mov_b32_e32 v42, v0
	v_mov_b32_e32 v43, v0
	v_mov_b32_e32 v44, v0
	v_mov_b32_e32 v45, v0
	v_mov_b32_e32 v46, v0
	v_mov_b32_e32 v47, v0
	v_mov_b32_e32 v48, v0
	v_mov_b32_e32 v49, v0
	v_mov_b32_e32 v50, v0
	v_mov_b32_e32 v51, v0
	v_mov_b32_e32 v52, v0
	v_mov_b32_e32 v53, v0
	v_mov_b32_e32 v54, v0
	v_mov_b32_e32 v55, v0
	v_mov_b32_e32 v56, v0
	v_mov_b32_e32 v57, v0
	v_mov_b32_e32 v58, v0
	v_mov_b32_e32 v59, v0
	v_mov_b32_e32 v60, v0
	v_mov_b32_e32 v61, v0
	v_mov_b32_e32 v62, v0
	v_mov_b32_e32 v63, v0
	s_waitcnt vmcnt(0)
	v_mov_b32_e32 v96, v0
	v_mov_b32_e32 v97, v0
	v_mov_b32_e32 v98, v0
	v_mov_b32_e32 v99, v0
	v_mov_b32_e32 v100, v0
	v_mov_b32_e32 v101, v0
	v_mov_b32_e32 v102, v0
	v_mov_b32_e32 v103, v0
	v_mov_b32_e32 v104, v0
	v_mov_b32_e32 v105, v0
	v_mov_b32_e32 v106, v0
	v_mov_b32_e32 v107, v0
	v_mov_b32_e32 v108, v0
	v_mov_b32_e32 v109, v0
	v_mov_b32_e32 v110, v0
	v_mov_b32_e32 v111, v0
	v_mov_b32_e32 v112, v0
	v_mov_b32_e32 v113, v0
	v_mov_b32_e32 v114, v0
	v_mov_b32_e32 v115, v0
	v_mov_b32_e32 v116, v0
	v_mov_b32_e32 v117, v0
	v_mov_b32_e32 v118, v0
	v_mov_b32_e32 v119, v0
	v_mov_b32_e32 v120, v0
	v_mov_b32_e32 v121, v0
	v_mov_b32_e32 v122, v0
	v_mov_b32_e32 v123, v0
	v_mov_b32_e32 v124, v0
	v_mov_b32_e32 v125, v0
	v_mov_b32_e32 v126, v0
	v_mov_b32_e32 v127, v0
	.p2align	6

; template <class Epi>
; DI void gemm_phase(LAS unsigned char* lds, const Gemm g, const StaticOrder& S, const Epi& E) {
;     ...
;         for (int a = 0; a < 2; ++a)
; #pragma unroll
;             for (int b = 0; b < 2; ++b)
; #pragma unroll
;                 for (int m = 0; m < 4; ++m)
; #pragma unroll
;                     for (int n = 0; n < 2; ++n) acc[a][b][m][n] = (f32x4){0.f, 0.f, 0.f, 0.f};
.LBB0_133:
	s_add_u32 s4, s18, 0x100
	v_mov_b32_e32 v0, 0
	s_addc_u32 s5, s19, 0
	s_mov_b32 s33, -2
	v_mov_b32_e32 v1, v0
	v_mov_b32_e32 v2, v0
	v_mov_b32_e32 v3, v0
	v_mov_b32_e32 v4, v0
	v_mov_b32_e32 v5, v0
	v_mov_b32_e32 v6, v0
	v_mov_b32_e32 v7, v0
	v_mov_b32_e32 v8, v0
	v_mov_b32_e32 v9, v0
	v_mov_b32_e32 v10, v0
	v_mov_b32_e32 v11, v0
	v_mov_b32_e32 v12, v0
	v_mov_b32_e32 v13, v0
	v_mov_b32_e32 v14, v0
	v_mov_b32_e32 v15, v0
	v_mov_b32_e32 v16, v0
	v_mov_b32_e32 v17, v0
	v_mov_b32_e32 v18, v0
	v_mov_b32_e32 v19, v0
	v_mov_b32_e32 v20, v0
	v_mov_b32_e32 v21, v0
	v_mov_b32_e32 v22, v0
	v_mov_b32_e32 v23, v0
	v_mov_b32_e32 v24, v0
	v_mov_b32_e32 v25, v0
	v_mov_b32_e32 v26, v0
	v_mov_b32_e32 v27, v0
	v_mov_b32_e32 v28, v0
	v_mov_b32_e32 v29, v0
	v_mov_b32_e32 v30, v0
	v_mov_b32_e32 v31, v0
	v_mov_b32_e32 v64, v0
	v_mov_b32_e32 v65, v0
	v_mov_b32_e32 v66, v0
	v_mov_b32_e32 v67, v0
	v_mov_b32_e32 v68, v0
	v_mov_b32_e32 v69, v0
	v_mov_b32_e32 v70, v0
	v_mov_b32_e32 v71, v0
	v_mov_b32_e32 v72, v0
	v_mov_b32_e32 v73, v0
	v_mov_b32_e32 v74, v0
	v_mov_b32_e32 v75, v0
	v_mov_b32_e32 v76, v0
	v_mov_b32_e32 v77, v0
	v_mov_b32_e32 v78, v0
	v_mov_b32_e32 v79, v0
	v_mov_b32_e32 v80, v0
	v_mov_b32_e32 v81, v0
	v_mov_b32_e32 v82, v0
	v_mov_b32_e32 v83, v0
	v_mov_b32_e32 v84, v0
	v_mov_b32_e32 v85, v0
	v_mov_b32_e32 v86, v0
	v_mov_b32_e32 v87, v0
	v_mov_b32_e32 v88, v0
	v_mov_b32_e32 v89, v0
	v_mov_b32_e32 v90, v0
	v_mov_b32_e32 v91, v0
	v_mov_b32_e32 v92, v0
	v_mov_b32_e32 v93, v0
	v_mov_b32_e32 v94, v0
	v_mov_b32_e32 v95, v0
	v_mov_b32_e32 v32, v0
	v_mov_b32_e32 v33, v0
	v_mov_b32_e32 v34, v0
	v_mov_b32_e32 v35, v0
	v_mov_b32_e32 v36, v0
	v_mov_b32_e32 v37, v0
	v_mov_b32_e32 v38, v0
	v_mov_b32_e32 v39, v0
	v_mov_b32_e32 v40, v0
	v_mov_b32_e32 v41, v0
	v_mov_b32_e32 v42, v0
	v_mov_b32_e32 v43, v0
	v_mov_b32_e32 v44, v0
	v_mov_b32_e32 v45, v0
	v_mov_b32_e32 v46, v0
	v_mov_b32_e32 v47, v0
	v_mov_b32_e32 v48, v0
	v_mov_b32_e32 v49, v0
	v_mov_b32_e32 v50, v0
	v_mov_b32_e32 v51, v0
	v_mov_b32_e32 v52, v0
	v_mov_b32_e32 v53, v0
	v_mov_b32_e32 v54, v0
	v_mov_b32_e32 v55, v0
	v_mov_b32_e32 v56, v0
	v_mov_b32_e32 v57, v0
	v_mov_b32_e32 v58, v0
	v_mov_b32_e32 v59, v0
	v_mov_b32_e32 v60, v0
	v_mov_b32_e32 v61, v0
	v_mov_b32_e32 v62, v0
	v_mov_b32_e32 v63, v0
	v_mov_b32_e32 v104, v0
	v_mov_b32_e32 v105, v0
	v_mov_b32_e32 v106, v0
	v_mov_b32_e32 v107, v0
	v_mov_b32_e32 v108, v0
	v_mov_b32_e32 v109, v0
	v_mov_b32_e32 v110, v0
	v_mov_b32_e32 v111, v0
	v_mov_b32_e32 v112, v0
	v_mov_b32_e32 v113, v0
	v_mov_b32_e32 v114, v0
	v_mov_b32_e32 v115, v0
	v_mov_b32_e32 v116, v0
	v_mov_b32_e32 v117, v0
	v_mov_b32_e32 v118, v0
	v_mov_b32_e32 v119, v0
	v_mov_b32_e32 v120, v0
	v_mov_b32_e32 v121, v0
	v_mov_b32_e32 v122, v0
	v_mov_b32_e32 v123, v0
	v_mov_b32_e32 v124, v0
	v_mov_b32_e32 v125, v0
	v_mov_b32_e32 v126, v0
	v_mov_b32_e32 v127, v0
	v_mov_b32_e32 v128, v0
	v_mov_b32_e32 v129, v0
	v_mov_b32_e32 v130, v0
	v_mov_b32_e32 v131, v0
	v_mov_b32_e32 v132, v0
	v_mov_b32_e32 v133, v0
	v_mov_b32_e32 v134, v0
	v_mov_b32_e32 v135, v0
	.p2align	6

; template <class Epi>
; DI void gemm_phase(LAS unsigned char* lds, const Gemm g, const StaticOrder& S, const Epi& E) {
;     ...
;         const bool has_next = S.next(ui + 1, nxt);
;         const char* nA = has_next ? (const char*)g.A + (size_t)nxt.pm * tstep : cA; const char* nB = has_next ? (const char*)g.Bt + (size_t)nxt.pn * tstep : cB;
;         for (int t = 0; t < nt; t += 2) {
;     ...
;         for (int a = 0; a < 2; ++a)
; #pragma unroll
;             for (int b = 0; b < 2; ++b)
; #pragma unroll
;                 for (int m = 0; m < 4; ++m)
; #pragma unroll
;                     for (int n = 0; n < 2; ++n) acc[a][b][m][n] = (f32x4){0.f, 0.f, 0.f, 0.f};
.LBB0_201:
	s_ashr_i32 s13, s12, 31
	v_mov_b64_e32 v[0:1], 0x6c0
	s_lshl_b64 s[4:5], s[12:13], 20
	v_cmp_lt_i64_e32 vcc, s[14:15], v[0:1]
	s_add_u32 s14, s92, s4
	s_addc_u32 s15, s93, s5
	s_and_b64 s[4:5], vcc, exec
	s_cselect_b32 s4, s15, s9
	s_cselect_b32 s5, s14, s8
	s_ashr_i32 s11, s10, 31
	s_lshl_b64 s[16:17], s[10:11], 20
	s_add_u32 s16, s23, s16
	s_addc_u32 s17, s24, s17
	s_and_b64 s[20:21], vcc, exec
	s_cselect_b32 s11, s17, s19
	s_cselect_b32 s13, s16, s18
	s_add_u32 s8, s8, 0x80080
	s_addc_u32 s9, s9, 0
	s_add_u32 s33, s18, 0x100
	v_mov_b32_e32 v0, 0
	s_addc_u32 s35, s19, 0
	s_mov_b32 s36, -2
	v_mov_b32_e32 v1, v0
	v_mov_b32_e32 v2, v0
	v_mov_b32_e32 v3, v0
	v_mov_b32_e32 v4, v0
	v_mov_b32_e32 v5, v0
	v_mov_b32_e32 v6, v0
	v_mov_b32_e32 v7, v0
	v_mov_b32_e32 v16, v0
	v_mov_b32_e32 v17, v0
	v_mov_b32_e32 v18, v0
	v_mov_b32_e32 v19, v0
	v_mov_b32_e32 v20, v0
	v_mov_b32_e32 v21, v0
	v_mov_b32_e32 v22, v0
	v_mov_b32_e32 v23, v0
	v_mov_b32_e32 v32, v0
	v_mov_b32_e32 v33, v0
	v_mov_b32_e32 v34, v0
	v_mov_b32_e32 v35, v0
	v_mov_b32_e32 v36, v0
	v_mov_b32_e32 v37, v0
	v_mov_b32_e32 v38, v0
	v_mov_b32_e32 v39, v0
	v_mov_b32_e32 v48, v0
	v_mov_b32_e32 v49, v0
	v_mov_b32_e32 v50, v0
	v_mov_b32_e32 v51, v0
	v_mov_b32_e32 v52, v0
	v_mov_b32_e32 v53, v0
	v_mov_b32_e32 v54, v0
	v_mov_b32_e32 v55, v0
	v_mov_b32_e32 v8, v0
	v_mov_b32_e32 v9, v0
	v_mov_b32_e32 v10, v0
	v_mov_b32_e32 v11, v0
	v_mov_b32_e32 v12, v0
	v_mov_b32_e32 v13, v0
	v_mov_b32_e32 v14, v0
	v_mov_b32_e32 v15, v0
	v_mov_b32_e32 v24, v0
	v_mov_b32_e32 v25, v0
	v_mov_b32_e32 v26, v0
	v_mov_b32_e32 v27, v0
	v_mov_b32_e32 v28, v0
	v_mov_b32_e32 v29, v0
	v_mov_b32_e32 v30, v0
	v_mov_b32_e32 v31, v0
	v_mov_b32_e32 v40, v0
	v_mov_b32_e32 v41, v0
	v_mov_b32_e32 v42, v0
	v_mov_b32_e32 v43, v0
	v_mov_b32_e32 v44, v0
	v_mov_b32_e32 v45, v0
	v_mov_b32_e32 v46, v0
	v_mov_b32_e32 v47, v0
	v_mov_b32_e32 v56, v0
	v_mov_b32_e32 v57, v0
	v_mov_b32_e32 v58, v0
	v_mov_b32_e32 v59, v0
	v_mov_b32_e32 v60, v0
	v_mov_b32_e32 v61, v0
	v_mov_b32_e32 v62, v0
	v_mov_b32_e32 v63, v0
	v_mov_b32_e32 v64, v0
	v_mov_b32_e32 v65, v0
	v_mov_b32_e32 v66, v0
	v_mov_b32_e32 v67, v0
	v_mov_b32_e32 v68, v0
	v_mov_b32_e32 v69, v0
	v_mov_b32_e32 v70, v0
	v_mov_b32_e32 v71, v0
	v_mov_b32_e32 v80, v0
	v_mov_b32_e32 v81, v0
	v_mov_b32_e32 v82, v0
	v_mov_b32_e32 v83, v0
	v_mov_b32_e32 v84, v0
	v_mov_b32_e32 v85, v0
	v_mov_b32_e32 v86, v0
	v_mov_b32_e32 v87, v0
	v_mov_b32_e32 v96, v0
	v_mov_b32_e32 v97, v0
	v_mov_b32_e32 v98, v0
	v_mov_b32_e32 v99, v0
	v_mov_b32_e32 v100, v0
	v_mov_b32_e32 v101, v0
	v_mov_b32_e32 v102, v0
	v_mov_b32_e32 v103, v0
	v_mov_b32_e32 v112, v0
	v_mov_b32_e32 v113, v0
	v_mov_b32_e32 v114, v0
	v_mov_b32_e32 v115, v0
	v_mov_b32_e32 v116, v0
	v_mov_b32_e32 v117, v0
	v_mov_b32_e32 v118, v0
	v_mov_b32_e32 v119, v0
	v_mov_b32_e32 v72, v0
	v_mov_b32_e32 v73, v0
	v_mov_b32_e32 v74, v0
	v_mov_b32_e32 v75, v0
	v_mov_b32_e32 v76, v0
	v_mov_b32_e32 v77, v0
	v_mov_b32_e32 v78, v0
	v_mov_b32_e32 v79, v0
	v_mov_b32_e32 v88, v0
	v_mov_b32_e32 v89, v0
	v_mov_b32_e32 v90, v0
	v_mov_b32_e32 v91, v0
	v_mov_b32_e32 v92, v0
	v_mov_b32_e32 v93, v0
	v_mov_b32_e32 v94, v0
	v_mov_b32_e32 v95, v0
	v_mov_b32_e32 v104, v0
	v_mov_b32_e32 v105, v0
	v_mov_b32_e32 v106, v0
	v_mov_b32_e32 v107, v0
	v_mov_b32_e32 v108, v0
	v_mov_b32_e32 v109, v0
	v_mov_b32_e32 v110, v0
	v_mov_b32_e32 v111, v0
	v_mov_b32_e32 v120, v0
	v_mov_b32_e32 v121, v0
	v_mov_b32_e32 v122, v0
	v_mov_b32_e32 v123, v0
	v_mov_b32_e32 v124, v0
	v_mov_b32_e32 v125, v0
	v_mov_b32_e32 v126, v0
	v_mov_b32_e32 v127, v0
	.p2align	6

; template <class Epi>
; DI void gemm_phase(LAS unsigned char* lds, const Gemm g, const StaticOrder& S, const Epi& E) {
;     ...
;         const bool has_next = S.next(ui + 1, nxt);
;         const char* nA = has_next ? (const char*)g.A + (size_t)nxt.pm * tstep : cA; const char* nB = has_next ? (const char*)g.Bt + (size_t)nxt.pn * tstep : cB;
;         for (int t = 0; t < nt; t += 2) {
;     ...
;         for (int a = 0; a < 2; ++a)
; #pragma unroll
;             for (int b = 0; b < 2; ++b)
; #pragma unroll
;                 for (int m = 0; m < 4; ++m)
; #pragma unroll
;                     for (int n = 0; n < 2; ++n) acc[a][b][m][n] = (f32x4){0.f, 0.f, 0.f, 0.f};
.LBB0_230:
	s_ashr_i32 s11, s10, 31
	s_lshl_b64 s[4:5], s[10:11], 20
	v_cmp_lt_i64_e32 vcc, s[12:13], v[166:167]
	s_add_u32 s12, s92, s4
	s_addc_u32 s13, s93, s5
	s_and_b64 s[4:5], vcc, exec
	s_cselect_b32 s4, s13, s17
	s_cselect_b32 s5, s12, s16
	s_ashr_i32 s9, s8, 31
	s_lshl_b64 s[14:15], s[8:9], 20
	s_add_u32 s14, s3, s14
	s_addc_u32 s15, s22, s15
	s_and_b64 s[20:21], vcc, exec
	s_cselect_b32 s9, s15, s19
	s_cselect_b32 s11, s14, s18
	s_add_u32 s16, s16, 0x80080
	s_addc_u32 s17, s17, 0
	s_add_u32 s34, s18, 0x100
	v_mov_b32_e32 v0, 0
	s_addc_u32 s35, s19, 0
	s_mov_b32 s36, -2
	v_mov_b32_e32 v1, v0
	v_mov_b32_e32 v2, v0
	v_mov_b32_e32 v3, v0
	v_mov_b32_e32 v4, v0
	v_mov_b32_e32 v5, v0
	v_mov_b32_e32 v6, v0
	v_mov_b32_e32 v7, v0
	v_mov_b32_e32 v8, v0
	v_mov_b32_e32 v9, v0
	v_mov_b32_e32 v10, v0
	v_mov_b32_e32 v11, v0
	v_mov_b32_e32 v12, v0
	v_mov_b32_e32 v13, v0
	v_mov_b32_e32 v14, v0
	v_mov_b32_e32 v15, v0
	v_mov_b32_e32 v24, v0
	v_mov_b32_e32 v25, v0
	v_mov_b32_e32 v26, v0
	v_mov_b32_e32 v27, v0
	v_mov_b32_e32 v28, v0
	v_mov_b32_e32 v29, v0
	v_mov_b32_e32 v30, v0
	v_mov_b32_e32 v31, v0
	v_mov_b32_e32 v40, v0
	v_mov_b32_e32 v41, v0
	v_mov_b32_e32 v42, v0
	v_mov_b32_e32 v43, v0
	v_mov_b32_e32 v44, v0
	v_mov_b32_e32 v45, v0
	v_mov_b32_e32 v46, v0
	v_mov_b32_e32 v47, v0
	v_mov_b32_e32 v16, v0
	v_mov_b32_e32 v17, v0
	v_mov_b32_e32 v18, v0
	v_mov_b32_e32 v19, v0
	v_mov_b32_e32 v20, v0
	v_mov_b32_e32 v21, v0
	v_mov_b32_e32 v22, v0
	v_mov_b32_e32 v23, v0
	v_mov_b32_e32 v32, v0
	v_mov_b32_e32 v33, v0
	v_mov_b32_e32 v34, v0
	v_mov_b32_e32 v35, v0
	v_mov_b32_e32 v36, v0
	v_mov_b32_e32 v37, v0
	v_mov_b32_e32 v38, v0
	v_mov_b32_e32 v39, v0
	v_mov_b32_e32 v48, v0
	v_mov_b32_e32 v49, v0
	v_mov_b32_e32 v50, v0
	v_mov_b32_e32 v51, v0
	v_mov_b32_e32 v52, v0
	v_mov_b32_e32 v53, v0
	v_mov_b32_e32 v54, v0
	v_mov_b32_e32 v55, v0
	v_mov_b32_e32 v56, v0
	v_mov_b32_e32 v57, v0
	v_mov_b32_e32 v58, v0
	v_mov_b32_e32 v59, v0
	v_mov_b32_e32 v60, v0
	v_mov_b32_e32 v61, v0
	v_mov_b32_e32 v62, v0
	v_mov_b32_e32 v63, v0
	v_mov_b32_e32 v64, v0
	v_mov_b32_e32 v65, v0
	v_mov_b32_e32 v66, v0
	v_mov_b32_e32 v67, v0
	v_mov_b32_e32 v68, v0
	v_mov_b32_e32 v69, v0
	v_mov_b32_e32 v70, v0
	v_mov_b32_e32 v71, v0
	v_mov_b32_e32 v72, v0
	v_mov_b32_e32 v73, v0
	v_mov_b32_e32 v74, v0
	v_mov_b32_e32 v75, v0
	v_mov_b32_e32 v76, v0
	v_mov_b32_e32 v77, v0
	v_mov_b32_e32 v78, v0
	v_mov_b32_e32 v79, v0
	v_mov_b32_e32 v88, v0
	v_mov_b32_e32 v89, v0
	v_mov_b32_e32 v90, v0
	v_mov_b32_e32 v91, v0
	v_mov_b32_e32 v92, v0
	v_mov_b32_e32 v93, v0
	v_mov_b32_e32 v94, v0
	v_mov_b32_e32 v95, v0
	v_mov_b32_e32 v104, v0
	v_mov_b32_e32 v105, v0
	v_mov_b32_e32 v106, v0
	v_mov_b32_e32 v107, v0
	v_mov_b32_e32 v108, v0
	v_mov_b32_e32 v109, v0
	v_mov_b32_e32 v110, v0
	v_mov_b32_e32 v111, v0
	v_mov_b32_e32 v80, v0
	v_mov_b32_e32 v81, v0
	v_mov_b32_e32 v82, v0
	v_mov_b32_e32 v83, v0
	v_mov_b32_e32 v84, v0
	v_mov_b32_e32 v85, v0
	v_mov_b32_e32 v86, v0
	v_mov_b32_e32 v87, v0
	v_mov_b32_e32 v96, v0
	v_mov_b32_e32 v97, v0
	v_mov_b32_e32 v98, v0
	v_mov_b32_e32 v99, v0
	v_mov_b32_e32 v100, v0
	v_mov_b32_e32 v101, v0
	v_mov_b32_e32 v102, v0
	v_mov_b32_e32 v103, v0
	v_mov_b32_e32 v112, v0
	v_mov_b32_e32 v113, v0
	v_mov_b32_e32 v114, v0
	v_mov_b32_e32 v115, v0
	v_mov_b32_e32 v116, v0
	v_mov_b32_e32 v117, v0
	v_mov_b32_e32 v118, v0
	v_mov_b32_e32 v119, v0
	v_mov_b32_e32 v120, v0
	v_mov_b32_e32 v121, v0
	v_mov_b32_e32 v122, v0
	v_mov_b32_e32 v123, v0
	v_mov_b32_e32 v124, v0
	v_mov_b32_e32 v125, v0
	v_mov_b32_e32 v126, v0
	v_mov_b32_e32 v127, v0
	.p2align	6

; template <class Epi>
; DI void gemm_phase(LAS unsigned char* lds, const Gemm g, const StaticOrder& S, const Epi& E) {
;     ...
;         const bool has_next = S.next(ui + 1, nxt);
;         const char* nA = has_next ? (const char*)g.A + (size_t)nxt.pm * tstep : cA; const char* nB = has_next ? (const char*)g.Bt + (size_t)nxt.pn * tstep : cB;
;         for (int t = 0; t < nt; t += 2) {
;     ...
;         for (int a = 0; a < 2; ++a)
; #pragma unroll
;             for (int b = 0; b < 2; ++b)
; #pragma unroll
;                 for (int m = 0; m < 4; ++m)
; #pragma unroll
;                     for (int n = 0; n < 2; ++n) acc[a][b][m][n] = (f32x4){0.f, 0.f, 0.f, 0.f};
.LBB0_319:
	s_ashr_i32 s11, s10, 31
	s_lshl_b64 s[4:5], s[10:11], 20
	v_cmp_lt_i64_e32 vcc, s[20:21], v[160:161]
	s_add_u32 s20, s52, s4
	s_addc_u32 s21, s53, s5
	s_and_b64 s[4:5], vcc, exec
	s_cselect_b32 s4, s21, s25
	s_cselect_b32 s5, s20, s24
	s_ashr_i32 s9, s8, 31
	s_lshl_b64 s[22:23], s[8:9], 20
	s_add_u32 s22, s35, s22
	s_addc_u32 s23, s36, s23
	s_and_b64 s[28:29], vcc, exec
	s_cselect_b32 s9, s23, s27
	s_cselect_b32 s11, s22, s26
	s_add_u32 s33, s26, 0x100
	v_mov_b32_e32 v0, 0
	s_addc_u32 s45, s27, 0
	s_mov_b32 s46, -2
	v_mov_b32_e32 v1, v0
	v_mov_b32_e32 v2, v0
	v_mov_b32_e32 v3, v0
	v_mov_b32_e32 v4, v0
	v_mov_b32_e32 v5, v0
	v_mov_b32_e32 v6, v0
	v_mov_b32_e32 v7, v0
	v_mov_b32_e32 v8, v0
	v_mov_b32_e32 v9, v0
	v_mov_b32_e32 v10, v0
	v_mov_b32_e32 v11, v0
	v_mov_b32_e32 v12, v0
	v_mov_b32_e32 v13, v0
	v_mov_b32_e32 v14, v0
	v_mov_b32_e32 v15, v0
	v_mov_b32_e32 v16, v0
	v_mov_b32_e32 v17, v0
	v_mov_b32_e32 v18, v0
	v_mov_b32_e32 v19, v0
	v_mov_b32_e32 v20, v0
	v_mov_b32_e32 v21, v0
	v_mov_b32_e32 v22, v0
	v_mov_b32_e32 v23, v0
	v_mov_b32_e32 v24, v0
	v_mov_b32_e32 v25, v0
	v_mov_b32_e32 v26, v0
	v_mov_b32_e32 v27, v0
	v_mov_b32_e32 v28, v0
	v_mov_b32_e32 v29, v0
	v_mov_b32_e32 v30, v0
	v_mov_b32_e32 v31, v0
	v_mov_b32_e32 v64, v0
	v_mov_b32_e32 v65, v0
	v_mov_b32_e32 v66, v0
	v_mov_b32_e32 v67, v0
	v_mov_b32_e32 v68, v0
	v_mov_b32_e32 v69, v0
	v_mov_b32_e32 v70, v0
	v_mov_b32_e32 v71, v0
	v_mov_b32_e32 v72, v0
	v_mov_b32_e32 v73, v0
	v_mov_b32_e32 v74, v0
	v_mov_b32_e32 v75, v0
	v_mov_b32_e32 v76, v0
	v_mov_b32_e32 v77, v0
	v_mov_b32_e32 v78, v0
	v_mov_b32_e32 v79, v0
	v_mov_b32_e32 v80, v0
	v_mov_b32_e32 v81, v0
	v_mov_b32_e32 v82, v0
	v_mov_b32_e32 v83, v0
	v_mov_b32_e32 v84, v0
	v_mov_b32_e32 v85, v0
	v_mov_b32_e32 v86, v0
	v_mov_b32_e32 v87, v0
	v_mov_b32_e32 v88, v0
	v_mov_b32_e32 v89, v0
	v_mov_b32_e32 v90, v0
	v_mov_b32_e32 v91, v0
	v_mov_b32_e32 v92, v0
	v_mov_b32_e32 v93, v0
	v_mov_b32_e32 v94, v0
	v_mov_b32_e32 v95, v0
	v_mov_b32_e32 v32, v0
	v_mov_b32_e32 v33, v0
	v_mov_b32_e32 v34, v0
	v_mov_b32_e32 v35, v0
	v_mov_b32_e32 v36, v0
	v_mov_b32_e32 v37, v0
	v_mov_b32_e32 v38, v0
	v_mov_b32_e32 v39, v0
	v_mov_b32_e32 v40, v0
	v_mov_b32_e32 v41, v0
	v_mov_b32_e32 v42, v0
	v_mov_b32_e32 v43, v0
	v_mov_b32_e32 v44, v0
	v_mov_b32_e32 v45, v0
	v_mov_b32_e32 v46, v0
	v_mov_b32_e32 v47, v0
	v_mov_b32_e32 v48, v0
	v_mov_b32_e32 v49, v0
	v_mov_b32_e32 v50, v0
	v_mov_b32_e32 v51, v0
	v_mov_b32_e32 v52, v0
	v_mov_b32_e32 v53, v0
	v_mov_b32_e32 v54, v0
	v_mov_b32_e32 v55, v0
	v_mov_b32_e32 v56, v0
	v_mov_b32_e32 v57, v0
	v_mov_b32_e32 v58, v0
	v_mov_b32_e32 v59, v0
	v_mov_b32_e32 v60, v0
	v_mov_b32_e32 v61, v0
	v_mov_b32_e32 v62, v0
	v_mov_b32_e32 v63, v0
	s_waitcnt vmcnt(0)
	v_mov_b32_e32 v96, v0
	v_mov_b32_e32 v97, v0
	v_mov_b32_e32 v98, v0
	v_mov_b32_e32 v99, v0
	v_mov_b32_e32 v100, v0
	v_mov_b32_e32 v101, v0
	v_mov_b32_e32 v102, v0
	v_mov_b32_e32 v103, v0
	v_mov_b32_e32 v104, v0
	v_mov_b32_e32 v105, v0
	v_mov_b32_e32 v106, v0
	v_mov_b32_e32 v107, v0
	v_mov_b32_e32 v108, v0
	v_mov_b32_e32 v109, v0
	v_mov_b32_e32 v110, v0
	v_mov_b32_e32 v111, v0
	v_mov_b32_e32 v112, v0
	v_mov_b32_e32 v113, v0
	v_mov_b32_e32 v114, v0
	v_mov_b32_e32 v115, v0
	v_mov_b32_e32 v116, v0
	v_mov_b32_e32 v117, v0
	v_mov_b32_e32 v118, v0
	v_mov_b32_e32 v119, v0
	v_mov_b32_e32 v120, v0
	v_mov_b32_e32 v121, v0
	v_mov_b32_e32 v122, v0
	v_mov_b32_e32 v123, v0
	v_mov_b32_e32 v124, v0
	v_mov_b32_e32 v125, v0
	v_mov_b32_e32 v126, v0
	v_mov_b32_e32 v127, v0
	.p2align	6
